# filters t-loop: exact power-of-two reciprocal instead of IEEE division, decay/exp chain interleaved with the FMA block
# baseline (speedup 1.0000x reference)
.LBB0_129:
	v_mov_b32_e32 v0, 0x21c90
	s_barrier
	s_lshr_b32 s100, s26, 1
	s_and_b32 s100, s100, 0x80
	s_lshl_b32 s101, s26, 1
	s_and_b32 s101, s101, 0x100
	s_or_b32 s100, s100, s101
	s_andn2_b32 s101, s26, 0x180
	s_or_b32 s100, s100, s101
	s_lshl_b32 s36, s100, 3
	v_add_u32_e32 v0, 0, v0
	s_ashr_i32 s8, s100, 8
	s_and_b32 s27, s36, 0x3f8
	s_and_b32 s33, s100, 0x80
	ds_read_b64 v[0:1], v0
	s_cmp_eq_u32 s33, 0
	s_cselect_b64 s[10:11], -1, 0
	s_and_b64 s[12:13], s[10:11], exec
	s_cselect_b32 s35, s20, 0x1000
	s_ashr_i32 s9, s8, 31
	s_waitcnt lgkmcnt(0)
	v_readfirstlane_b32 s17, v0
	s_lshl_b64 s[12:13], s[8:9], 18
	v_readfirstlane_b32 s16, v1
	s_add_u32 s12, s17, s12
	s_addc_u32 s13, s16, s13
	v_lshl_add_u64 v[0:1], s[12:13], 0, v[72:73]
	s_lshl_b32 s48, s27, 2
	v_lshl_add_u64 v[0:1], v[0:1], 0, s[48:49]
	v_lshl_add_u64 v[0:1], v[0:1], 0, v[74:75]
	global_load_dword v0, v[0:1], off
	v_mov_b32_e32 v1, 0x21ca0
	v_cmp_gt_i32_e32 vcc, s35, v66
	v_mov_b32_e32 v70, v71
	s_waitcnt vmcnt(0)
	ds_write_b32 v69, v0
	s_waitcnt lgkmcnt(0)
	s_barrier
	s_nop 0
	v_add_u32_e32 v0, 0, v1
	ds_read_b64 v[0:1], v0
	s_waitcnt lgkmcnt(0)
	v_readfirstlane_b32 s17, v1
	v_readfirstlane_b32 s16, v0
	s_and_saveexec_b64 s[12:13], vcc
	s_cbranch_execz .LBB0_133
	s_and_b32 s9, s36, 0x200
	s_lshl_b32 s37, s8, 10
	s_and_b32 s36, s36, 0x1f8
	s_or_b32 s9, s9, s37
	v_or_b32_e32 v0, s36, v68
	v_or_b32_e32 v0, s9, v0
	v_ashrrev_i32_e32 v1, 31, v0
	v_lshl_add_u64 v[0:1], v[0:1], 2, s[16:17]
	global_load_dword v2, v[0:1], off
	s_lshl_b32 s9, s100, 1
	s_lshr_b32 s40, s35, 1
	s_and_b32 s41, s9, 0x100
	s_and_b64 s[36:37], s[10:11], exec
	s_mul_i32 s39, s8, 0x1100
	s_cselect_b32 s36, 8, 12
	s_sub_i32 s9, 0, s40
	s_mul_hi_i32 s38, s8, 0x1100
	v_lshlrev_b32_e32 v0, s36, v68
	s_add_u32 s36, s41, s39
	v_cvt_f32_u32_e32 v132, s35
	s_addc_u32 s37, 0, s38
	v_lshl_add_u32 v133, v0, 2, v128
	v_lshl_add_u64 v[0:1], s[36:37], 0, v[66:67]
	v_lshlrev_b64 v[0:1], 8, v[0:1]
	v_mov_b32_e32 v70, 0
	s_mov_b64 s[16:17], 0
	v_lshl_add_u64 v[76:77], s[4:5], 0, v[0:1]
	v_mov_b32_e32 v135, v66
	s_waitcnt vmcnt(0)
	v_and_b32_e32 v134, 0x7fffffff, v2
	v_lshlrev_b32_e32 v26, 7, v68
	v_sub_u32_e32 v31, 0x7f000000, v132
	v_xor_b32_e32 v27, 0, v68
	v_lshl_add_u32 v27, v27, 2, v26
	v_add_u32_e32 v28, 0x400, v27
	ds_read2_b32 v[78:79], v27 offset1:8
	ds_read2_b32 v[80:81], v27 offset0:16 offset1:24
	ds_read2_b32 v[82:83], v28 offset1:8
	ds_read2_b32 v[84:85], v28 offset0:16 offset1:24
	v_xor_b32_e32 v29, 1, v68
	v_lshl_add_u32 v29, v29, 2, v26
	v_add_u32_e32 v30, 0x400, v29
	ds_read2_b32 v[86:87], v29 offset1:8
	ds_read2_b32 v[88:89], v29 offset0:16 offset1:24
	ds_read2_b32 v[90:91], v30 offset1:8
	ds_read2_b32 v[92:93], v30 offset0:16 offset1:24
	v_xor_b32_e32 v27, 2, v68
	v_lshl_add_u32 v27, v27, 2, v26
	v_add_u32_e32 v28, 0x400, v27
	ds_read2_b32 v[94:95], v27 offset1:8
	ds_read2_b32 v[96:97], v27 offset0:16 offset1:24
	ds_read2_b32 v[98:99], v28 offset1:8
	ds_read2_b32 v[100:101], v28 offset0:16 offset1:24
	v_xor_b32_e32 v29, 3, v68
	v_lshl_add_u32 v29, v29, 2, v26
	v_add_u32_e32 v30, 0x400, v29
	ds_read2_b32 v[102:103], v29 offset1:8
	ds_read2_b32 v[104:105], v29 offset0:16 offset1:24
	ds_read2_b32 v[106:107], v30 offset1:8
	ds_read2_b32 v[108:109], v30 offset0:16 offset1:24
	v_xor_b32_e32 v27, 4, v68
	v_lshl_add_u32 v27, v27, 2, v26
	v_add_u32_e32 v28, 0x400, v27
	ds_read2_b32 v[110:111], v27 offset1:8
	ds_read2_b32 v[112:113], v27 offset0:16 offset1:24
	ds_read2_b32 v[114:115], v28 offset1:8
	ds_read2_b32 v[116:117], v28 offset0:16 offset1:24
	v_xor_b32_e32 v29, 5, v68
	v_lshl_add_u32 v29, v29, 2, v26
	v_add_u32_e32 v30, 0x400, v29
	ds_read2_b32 v[118:119], v29 offset1:8
	ds_read2_b32 v[120:121], v29 offset0:16 offset1:24
	ds_read2_b32 v[122:123], v30 offset1:8
	ds_read2_b32 v[124:125], v30 offset0:16 offset1:24
	v_xor_b32_e32 v27, 6, v68
	v_lshl_add_u32 v27, v27, 2, v26
	v_add_u32_e32 v28, 0x400, v27
	ds_read2_b32 v[136:137], v27 offset1:8
	ds_read2_b32 v[138:139], v27 offset0:16 offset1:24
	ds_read2_b32 v[140:141], v28 offset1:8
	ds_read2_b32 v[142:143], v28 offset0:16 offset1:24
	v_xor_b32_e32 v29, 7, v68
	v_lshl_add_u32 v29, v29, 2, v26
	v_add_u32_e32 v30, 0x400, v29
	ds_read2_b32 v[144:145], v29 offset1:8
	ds_read2_b32 v[146:147], v29 offset0:16 offset1:24
	ds_read2_b32 v[148:149], v30 offset1:8
	ds_read2_b32 v[150:151], v30 offset0:16 offset1:24
	v_lshl_add_u64 v[24:25], v[74:75], 2, v[76:77]
	global_load_dwordx4 v[0:3], v[24:25], off offset:-248
	global_load_dwordx4 v[4:7], v[24:25], off offset:-120
	s_lshr_b32 s101, s35, 7
	s_waitcnt lgkmcnt(0)
.Lfilt_t_loop:
	v_lshl_add_u64 v[24:25], v[24:25], 0, s[6:7]
	global_load_dwordx4 v[8:11], v[24:25], off offset:-248
	global_load_dwordx4 v[12:15], v[24:25], off offset:-120
	s_waitcnt vmcnt(2)
	v_mul_f32_e32 v16, v0, v78
	v_mul_f32_e32 v17, v0, v86
	v_mul_f32_e32 v18, v0, v94
	v_add_u32_e32 v152, s9, v135
	v_mul_f32_e32 v19, v0, v102
	v_mul_f32_e32 v20, v0, v110
	v_mul_f32_e32 v21, v0, v118
	v_cvt_f32_i32_e32 v152, v152
	v_mul_f32_e32 v22, v0, v136
	v_mul_f32_e32 v23, v0, v144
	v_fmac_f32_e32 v16, v1, v79
	v_add_u32_e32 v135, 64, v135
	v_fmac_f32_e32 v17, v1, v87
	v_fmac_f32_e32 v18, v1, v95
	v_fmac_f32_e32 v19, v1, v103
	v_mul_f32_e64 v152, |v152|, v31
	v_fmac_f32_e32 v20, v1, v111
	v_fmac_f32_e32 v21, v1, v119
	v_fmac_f32_e32 v22, v1, v137
	v_mul_f32_e64 v152, v152, -v134
	v_fmac_f32_e32 v23, v1, v145
	v_fmac_f32_e32 v16, v2, v80
	v_fmac_f32_e32 v17, v2, v88
	v_mul_f32_e32 v153, 0x3fb8aa3b, v152
	v_fmac_f32_e32 v18, v2, v96
	v_fmac_f32_e32 v19, v2, v104
	v_fmac_f32_e32 v20, v2, v112
	v_fma_f32 v154, v152, s21, -v153
	v_fmac_f32_e32 v21, v2, v120
	v_fmac_f32_e32 v22, v2, v138
	v_fmac_f32_e32 v23, v2, v146
	v_rndne_f32_e32 v155, v153
	v_fmac_f32_e32 v16, v3, v81
	v_fmac_f32_e32 v17, v3, v89
	v_fmac_f32_e32 v18, v3, v97
	v_fmac_f32_e32 v154, 0x32a5705f, v152
	v_fmac_f32_e32 v19, v3, v105
	v_fmac_f32_e32 v20, v3, v113
	v_fmac_f32_e32 v21, v3, v121
	v_sub_f32_e32 v153, v153, v155
	v_fmac_f32_e32 v22, v3, v139
	v_fmac_f32_e32 v23, v3, v147
	v_fmac_f32_e32 v16, v4, v82
	v_add_f32_e32 v153, v153, v154
	v_fmac_f32_e32 v17, v4, v90
	v_fmac_f32_e32 v18, v4, v98
	v_fmac_f32_e32 v19, v4, v106
	v_cvt_i32_f32_e32 v155, v155
	v_fmac_f32_e32 v20, v4, v114
	v_fmac_f32_e32 v21, v4, v122
	v_fmac_f32_e32 v22, v4, v140
	v_exp_f32_e32 v153, v153
	v_fmac_f32_e32 v23, v4, v148
	v_fmac_f32_e32 v16, v5, v83
	v_fmac_f32_e32 v17, v5, v91
	v_cmp_ngt_f32_e32 vcc, s22, v152
	v_fmac_f32_e32 v18, v5, v99
	v_fmac_f32_e32 v19, v5, v107
	v_fmac_f32_e32 v20, v5, v115
	v_ldexp_f32 v153, v153, v155
	v_fmac_f32_e32 v21, v5, v123
	v_fmac_f32_e32 v22, v5, v141
	v_fmac_f32_e32 v23, v5, v149
	v_cndmask_b32_e32 v153, 0, v153, vcc
	v_fmac_f32_e32 v16, v6, v84
	v_fmac_f32_e32 v17, v6, v92
	v_fmac_f32_e32 v18, v6, v100
	v_cmp_nlt_f32_e32 vcc, s23, v152
	v_fmac_f32_e32 v19, v6, v108
	v_fmac_f32_e32 v20, v6, v116
	v_fmac_f32_e32 v21, v6, v124
	v_cndmask_b32_e32 v152, v130, v153, vcc
	v_fmac_f32_e32 v22, v6, v142
	v_fmac_f32_e32 v23, v6, v150
	v_fmac_f32_e32 v16, v7, v85
	v_fmac_f32_e32 v17, v7, v93
	v_fmac_f32_e32 v18, v7, v101
	v_fmac_f32_e32 v19, v7, v109
	v_fmac_f32_e32 v20, v7, v117
	v_fmac_f32_e32 v21, v7, v125
	v_fmac_f32_e32 v22, v7, v143
	v_fmac_f32_e32 v23, v7, v151
	s_nop 1
	v_add_f32_dpp v16, v23, v16 row_half_mirror row_mask:0xf bank_mask:0xf
	v_add_f32_dpp v17, v22, v17 row_half_mirror row_mask:0xf bank_mask:0xf
	v_add_f32_dpp v18, v21, v18 row_half_mirror row_mask:0xf bank_mask:0xf
	v_add_f32_dpp v19, v20, v19 row_half_mirror row_mask:0xf bank_mask:0xf
	s_nop 0
	v_add_f32_dpp v16, v18, v16 quad_perm:[2,3,0,1] row_mask:0xf bank_mask:0xf
	v_add_f32_dpp v17, v19, v17 quad_perm:[2,3,0,1] row_mask:0xf bank_mask:0xf
	s_nop 1
	v_add_f32_dpp v16, v17, v16 quad_perm:[1,0,3,2] row_mask:0xf bank_mask:0xf
	v_mul_f32_e32 v26, v152, v16
	ds_write_b32 v133, v26
	v_add_f32_e64 v70, v70, |v26|
	v_add_u32_e32 v133, 0x100, v133
	s_cmp_eq_u32 s101, 1
	s_cselect_b32 vcc_lo, 0, 0x4000
	s_mov_b32 vcc_hi, 0
	v_lshl_add_u64 v[24:25], v[24:25], 0, vcc
	global_load_dwordx4 v[0:3], v[24:25], off offset:-248
	global_load_dwordx4 v[4:7], v[24:25], off offset:-120
	s_waitcnt vmcnt(2)
	v_mul_f32_e32 v16, v8, v78
	v_mul_f32_e32 v17, v8, v86
	v_mul_f32_e32 v18, v8, v94
	v_add_u32_e32 v152, s9, v135
	v_mul_f32_e32 v19, v8, v102
	v_mul_f32_e32 v20, v8, v110
	v_mul_f32_e32 v21, v8, v118
	v_cvt_f32_i32_e32 v152, v152
	v_mul_f32_e32 v22, v8, v136
	v_mul_f32_e32 v23, v8, v144
	v_fmac_f32_e32 v16, v9, v79
	v_add_u32_e32 v135, 64, v135
	v_fmac_f32_e32 v17, v9, v87
	v_fmac_f32_e32 v18, v9, v95
	v_fmac_f32_e32 v19, v9, v103
	v_mul_f32_e64 v152, |v152|, v31
	v_fmac_f32_e32 v20, v9, v111
	v_fmac_f32_e32 v21, v9, v119
	v_fmac_f32_e32 v22, v9, v137
	v_mul_f32_e64 v152, v152, -v134
	v_fmac_f32_e32 v23, v9, v145
	v_fmac_f32_e32 v16, v10, v80
	v_fmac_f32_e32 v17, v10, v88
	v_mul_f32_e32 v153, 0x3fb8aa3b, v152
	v_fmac_f32_e32 v18, v10, v96
	v_fmac_f32_e32 v19, v10, v104
	v_fmac_f32_e32 v20, v10, v112
	v_fma_f32 v154, v152, s21, -v153
	v_fmac_f32_e32 v21, v10, v120
	v_fmac_f32_e32 v22, v10, v138
	v_fmac_f32_e32 v23, v10, v146
	v_rndne_f32_e32 v155, v153
	v_fmac_f32_e32 v16, v11, v81
	v_fmac_f32_e32 v17, v11, v89
	v_fmac_f32_e32 v18, v11, v97
	v_fmac_f32_e32 v154, 0x32a5705f, v152
	v_fmac_f32_e32 v19, v11, v105
	v_fmac_f32_e32 v20, v11, v113
	v_fmac_f32_e32 v21, v11, v121
	v_sub_f32_e32 v153, v153, v155
	v_fmac_f32_e32 v22, v11, v139
	v_fmac_f32_e32 v23, v11, v147
	v_fmac_f32_e32 v16, v12, v82
	v_add_f32_e32 v153, v153, v154
	v_fmac_f32_e32 v17, v12, v90
	v_fmac_f32_e32 v18, v12, v98
	v_fmac_f32_e32 v19, v12, v106
	v_cvt_i32_f32_e32 v155, v155
	v_fmac_f32_e32 v20, v12, v114
	v_fmac_f32_e32 v21, v12, v122
	v_fmac_f32_e32 v22, v12, v140
	v_exp_f32_e32 v153, v153
	v_fmac_f32_e32 v23, v12, v148
	v_fmac_f32_e32 v16, v13, v83
	v_fmac_f32_e32 v17, v13, v91
	v_cmp_ngt_f32_e32 vcc, s22, v152
	v_fmac_f32_e32 v18, v13, v99
	v_fmac_f32_e32 v19, v13, v107
	v_fmac_f32_e32 v20, v13, v115
	v_ldexp_f32 v153, v153, v155
	v_fmac_f32_e32 v21, v13, v123
	v_fmac_f32_e32 v22, v13, v141
	v_fmac_f32_e32 v23, v13, v149
	v_cndmask_b32_e32 v153, 0, v153, vcc
	v_fmac_f32_e32 v16, v14, v84
	v_fmac_f32_e32 v17, v14, v92
	v_fmac_f32_e32 v18, v14, v100
	v_cmp_nlt_f32_e32 vcc, s23, v152
	v_fmac_f32_e32 v19, v14, v108
	v_fmac_f32_e32 v20, v14, v116
	v_fmac_f32_e32 v21, v14, v124
	v_cndmask_b32_e32 v152, v130, v153, vcc
	v_fmac_f32_e32 v22, v14, v142
	v_fmac_f32_e32 v23, v14, v150
	v_fmac_f32_e32 v16, v15, v85
	v_fmac_f32_e32 v17, v15, v93
	v_fmac_f32_e32 v18, v15, v101
	v_fmac_f32_e32 v19, v15, v109
	v_fmac_f32_e32 v20, v15, v117
	v_fmac_f32_e32 v21, v15, v125
	v_fmac_f32_e32 v22, v15, v143
	v_fmac_f32_e32 v23, v15, v151
	s_nop 1
	v_add_f32_dpp v16, v23, v16 row_half_mirror row_mask:0xf bank_mask:0xf
	v_add_f32_dpp v17, v22, v17 row_half_mirror row_mask:0xf bank_mask:0xf
	v_add_f32_dpp v18, v21, v18 row_half_mirror row_mask:0xf bank_mask:0xf
	v_add_f32_dpp v19, v20, v19 row_half_mirror row_mask:0xf bank_mask:0xf
	s_nop 0
	v_add_f32_dpp v16, v18, v16 quad_perm:[2,3,0,1] row_mask:0xf bank_mask:0xf
	v_add_f32_dpp v17, v19, v17 quad_perm:[2,3,0,1] row_mask:0xf bank_mask:0xf
	s_nop 1
	v_add_f32_dpp v16, v17, v16 quad_perm:[1,0,3,2] row_mask:0xf bank_mask:0xf
	v_mul_f32_e32 v26, v152, v16
	ds_write_b32 v133, v26
	v_add_f32_e64 v70, v70, |v26|
	v_add_u32_e32 v133, 0x100, v133
	s_sub_u32 s101, s101, 1
	s_cmp_lg_u32 s101, 0
	s_cbranch_scc1 .Lfilt_t_loop
	s_waitcnt vmcnt(0)
	s_or_b64 exec, exec, s[16:17]
